# stack9 + one static s_setprio 1 for waves 4-7 during the G3 phase (reset at phase end)
# speedup vs baseline: 1.0002x; 1.0002x over previous
; __device__ __forceinline__ int opaque_tid() { int t = threadIdx.x; asm volatile("" : "+v"(t)); return t; }
; __device__ __forceinline__ void gla_g3(LAS unsigned char* lds, const bf16_t* P, const bf16_t* VAT, const bf16_t* DS, const float* BC, const float* gn, bf16_t* MIX) {
;     const int tid = opaque_tid(), lane = tid & 63, fr = lane & 15, g = lane >> 4;
;     const int wv = __builtin_amdgcn_readfirstlane(tid >> 6), rb = wv & 3, dvh = wv >> 2;
.LBB0_627:
	v_lshrrev_b32_e32 v100, 6, v250
	s_nop 0
	v_readfirstlane_b32 s98, v100
	s_nop 3
	s_cmp_lt_u32 s98, 4
	s_cbranch_scc1 .Lg3_prio_done
	s_setprio 1

; __device__ __forceinline__ void gla_g3(LAS unsigned char* lds, const bf16_t* P, const bf16_t* VAT, const bf16_t* DS, const float* BC, const float* gn, bf16_t* MIX) {
;     ...
;     asm volatile("s_waitcnt vmcnt(0)" ::: "memory");
;     __syncthreads();
; __device__ __forceinline__ void xcd_barrier(const XcdBarrier& b) {
;     asm volatile("s_waitcnt vmcnt(0)" ::: "memory");
;     __syncthreads();
;     if (threadIdx.x == 0) {
;         unsigned* bar = b.bar;
;         __builtin_amdgcn_s_waitcnt(0);
;         unsigned nloc = b.st[0], nx = b.st[1];
;         if (nloc == 0u) { xcd_barrier_complete(bar, b.x, nloc, nx); b.st[0] = nloc; b.st[1] = nx; }
.LBB0_649:
	s_setprio 0
	s_waitcnt vmcnt(0)
	s_waitcnt vmcnt(0)
	s_barrier
	s_waitcnt vmcnt(0)
	s_barrier
	s_and_saveexec_b64 s[0:1], s[68:69]
	s_cbranch_execz .LBB0_701
	v_readlane_b32 s2, v254, 23
	s_waitcnt vmcnt(0) expcnt(0) lgkmcnt(0)
	s_nop 0
	v_mov_b32_e32 v0, s2
	ds_read_b32 v2, v0
	v_readlane_b32 s2, v254, 24
	s_waitcnt lgkmcnt(0)
	v_cmp_ne_u32_e32 vcc, 0, v2
	v_mov_b32_e32 v0, s2
	ds_read_b32 v0, v0
	s_cbranch_vccnz .LBB0_665
	s_mov_b32 s2, 1
	s_branch .LBB0_653
